# v20 + attention: waves 4-7 take the per-step barrier 3 PV gaps earlier (persistent partial stagger of the two wave halves)
# speedup vs baseline: 1.0135x; 1.0135x over previous
; __device__ __forceinline__ void attn_unit(int b, int h, int qb, bool first, bool has_next, int nb, int nh, bf16_t* QO, const bf16_t* __restrict__ K, const bf16_t* __restrict__ V, float lam, char* shm) {
;     int tid = threadIdx.x; asm volatile("" : "+v"(tid));
;     const int lane = tid & 63, r32 = lane & 31, hi = lane >> 5; const int wid = __builtin_amdgcn_readfirstlane(tid >> 6);
; __global__ void __launch_bounds__(512, 2) fwd_kernel(Args args) {
;     ...
;         const float s1 = wave_sum(lam_q1[lane] * lam_k1[lane]), s2 = wave_sum(lam_q2[lane] * lam_k2[lane]);
;         const float lam = __expf(s1) - __expf(s2) + LAMBDA_INIT;
;         for (int i = 0; ; ++i) { const int L = i * G + vcu, NU = NBATCH * NH * (SEQ / 256); if (L >= NU) break;
;             const int bh = L >> 3, qb = L & 7, Ln = L + G, nbh = Ln >> 3;
;             att::attn_unit(bh >> 3, bh & 7, qb, i == 0, Ln < NU, nbh >> 3, nbh & 7, QO, KB, VB, lam, (char*)lds_raw); }
.LBB0_367:
	s_or_b64 exec, exec, s[0:1]
	v_lshlrev_b32_e32 v1, 2, v162
	s_barrier
	global_load_dword v2, v1, s[48:49]
	global_load_dword v3, v1, s[50:51]
	global_load_dword v4, v1, s[16:17]
	global_load_dword v5, v1, s[18:19]
	v_mbcnt_lo_u32_b32 v1, -1, 0
	v_mbcnt_hi_u32_b32 v6, -1, v1
	v_and_b32_e32 v1, 64, v6
	v_xor_b32_e32 v7, 1, v6
	v_add_u32_e32 v13, 64, v1
	v_cmp_lt_i32_e32 vcc, v7, v13
	v_xor_b32_e32 v8, 2, v6
	v_xor_b32_e32 v9, 4, v6
	v_cndmask_b32_e32 v1, v6, v7, vcc
	v_lshlrev_b32_e32 v1, 2, v1
	v_cmp_lt_i32_e32 vcc, v8, v13
	v_xor_b32_e32 v10, 8, v6
	v_xor_b32_e32 v11, 16, v6
	v_cndmask_b32_e32 v8, v6, v8, vcc
	v_lshlrev_b32_e32 v234, 2, v8
	v_cmp_lt_i32_e32 vcc, v9, v13
	v_xor_b32_e32 v12, 32, v6
	s_cmpk_gt_i32 s86, 0x5ff
	s_mov_b32 s1, 0
	s_waitcnt vmcnt(2)
	v_mul_f32_e32 v7, v2, v3
	ds_bpermute_b32 v7, v1, v7
	s_waitcnt vmcnt(0)
	v_mul_f32_e32 v14, v4, v5
	ds_bpermute_b32 v14, v1, v14
	s_waitcnt lgkmcnt(1)
	v_fmac_f32_e32 v7, v2, v3
	ds_bpermute_b32 v2, v234, v7
	s_waitcnt lgkmcnt(1)
	v_fmac_f32_e32 v14, v4, v5
	ds_bpermute_b32 v3, v234, v14
	v_cndmask_b32_e32 v4, v6, v9, vcc
	v_lshlrev_b32_e32 v235, 2, v4
	s_waitcnt lgkmcnt(1)
	v_add_f32_e32 v2, v7, v2
	ds_bpermute_b32 v4, v235, v2
	s_waitcnt lgkmcnt(1)
	v_add_f32_e32 v3, v14, v3
	ds_bpermute_b32 v5, v235, v3
	v_cmp_lt_i32_e32 vcc, v10, v13
	s_waitcnt lgkmcnt(1)
	v_add_f32_e32 v2, v2, v4
	v_cndmask_b32_e32 v7, v6, v10, vcc
	v_lshlrev_b32_e32 v236, 2, v7
	s_waitcnt lgkmcnt(0)
	v_add_f32_e32 v3, v3, v5
	ds_bpermute_b32 v4, v236, v2
	ds_bpermute_b32 v5, v236, v3
	v_cmp_lt_i32_e32 vcc, v11, v13
	s_waitcnt lgkmcnt(1)
	v_add_f32_e32 v2, v2, v4
	v_cndmask_b32_e32 v7, v6, v11, vcc
	v_lshlrev_b32_e32 v237, 2, v7
	s_waitcnt lgkmcnt(0)
	v_add_f32_e32 v3, v3, v5
	ds_bpermute_b32 v4, v237, v2
	ds_bpermute_b32 v5, v237, v3
	v_cmp_lt_i32_e32 vcc, v12, v13
	s_waitcnt lgkmcnt(1)
	v_add_f32_e32 v2, v2, v4
	v_cndmask_b32_e32 v6, v6, v12, vcc
	v_lshlrev_b32_e32 v6, 2, v6
	s_waitcnt lgkmcnt(0)
	v_add_f32_e32 v3, v3, v5
	ds_bpermute_b32 v4, v6, v2
	ds_bpermute_b32 v5, v6, v3
	s_cbranch_scc1 .LBB0_385
	s_waitcnt lgkmcnt(1)
	v_add_f32_e32 v2, v2, v4
	s_waitcnt lgkmcnt(0)
	v_add_f32_e32 v3, v3, v5
	v_mul_f32_e32 v2, 0x3fb8aa3b, v2
	v_mul_f32_e32 v3, 0x3fb8aa3b, v3
	v_exp_f32_e32 v2, v2
	v_exp_f32_e32 v3, v3
	s_add_u32 s56, s62, 0xd220000
	s_addc_u32 s57, s63, 0
	s_lshl_b32 s72, s86, 8
	s_lshl_b32 s73, s15, 8
	v_writelane_b32 v248, s78, 4
	v_sub_f32_e32 v2, v2, v3
	s_add_u32 s76, s62, 0x13220000
	s_mov_b32 s65, s80
	v_writelane_b32 v248, s79, 5
	v_add_f32_e32 v238, 0x3e4ccccd, v2
	s_addc_u32 s77, s63, 0
	s_movk_i32 s78, 0x1e0
	s_mov_b64 s[2:3], 0x800
	s_mov_b64 s[4:5], 0x20000
	s_mov_b64 s[8:9], 0x20800
	s_mov_b64 s[10:11], 0x3c0000
	s_mov_b64 s[16:17], 0x3c0800
	s_mov_b64 s[18:19], 0x3e0000
	s_mov_b64 s[20:21], 0x3e0800
	v_mov_b32_e32 v203, 0
	s_mov_b64 s[22:23], 0x40000
	s_mov_b64 s[24:25], 0x60000
	s_mov_b64 s[30:31], 0x80000
	s_mov_b64 s[44:45], 0x40800
	v_mov_b32_e32 v239, 0x358637bd
	s_movk_i32 s79, 0xffe0
	s_mov_b32 s0, s86
	s_mov_b32 s80, 0
	v_readfirstlane_b32 s98, v0
	s_lshr_b32 s98, s98, 6
	s_cmp_ge_u32 s98, 4
	s_cselect_b32 s98, 1, 0
	s_branch .LBB0_370

.LBB0_375:
	v_lshl_add_u32 v154, s60, 14, v241
	ds_read_b64_tr_b16 v[150:151], v154 offset:24576
	ds_read_b64_tr_b16 v[152:153], v154 offset:25088
	v_add_f32_e32 v106, v82, v83
	v_add_f32_e32 v106, v84, v106
	v_add_f32_e32 v106, v85, v106
	v_add_f32_e32 v106, v86, v106
	v_add_f32_e32 v106, v87, v106
	v_cvt_pk_bf16_f32 v174, v82, v83
	v_cvt_pk_bf16_f32 v175, v84, v85
	s_waitcnt lgkmcnt(9)
	v_mfma_f32_32x32x16_bf16 v[114:129], v[102:105], v[190:193], 0
	ds_read_b64_tr_b16 v[82:83], v154 offset:28672
	ds_read_b64_tr_b16 v[84:85], v154 offset:29184
	v_add_f32_e32 v102, v88, v106
	v_add_f32_e32 v102, v89, v102
	v_add_f32_e32 v102, v90, v102
	v_add_f32_e32 v155, v91, v102
	s_waitcnt lgkmcnt(10)
	v_mfma_f32_32x32x16_bf16 v[98:113], v[98:101], v[190:193], 0
	v_cvt_pk_bf16_f32 v176, v86, v87
	v_cvt_pk_bf16_f32 v177, v88, v89
	ds_read_b64_tr_b16 v[86:87], v154 offset:32768
	ds_read_b64_tr_b16 v[88:89], v154 offset:33280
	v_add_f32_e32 v155, v92, v155
	v_add_f32_e32 v155, v93, v155
	v_add_f32_e32 v155, v94, v155
	v_add_f32_e32 v155, v95, v155
	v_cvt_pk_bf16_f32 v170, v90, v91
	v_cvt_pk_bf16_f32 v171, v92, v93
	s_waitcnt lgkmcnt(11)
	v_mfma_f32_32x32x16_bf16 v[114:129], v[198:201], v[186:189], v[114:129]
	ds_read_b64_tr_b16 v[90:91], v154 offset:36864
	ds_read_b64_tr_b16 v[92:93], v154 offset:37376
	s_waitcnt lgkmcnt(12)
	v_mfma_f32_32x32x16_bf16 v[98:113], v[142:145], v[186:189], v[98:113]
	v_add_f32_e32 v155, v96, v155
	v_add_f32_e32 v155, v97, v155
	v_add_f32_e32 v155, v66, v155
	v_add_f32_e32 v155, v67, v155
	v_cvt_pk_bf16_f32 v172, v94, v95
	v_cvt_pk_bf16_f32 v173, v96, v97
	s_nop 0
	v_add_f32_e32 v94, v68, v155
	v_add_f32_e32 v94, v69, v94
	v_add_f32_e32 v94, v70, v94
	v_add_f32_e32 v94, v71, v94
	v_cvt_pk_bf16_f32 v166, v66, v67
	v_cvt_pk_bf16_f32 v167, v68, v69
	s_waitcnt lgkmcnt(11)
	v_mfma_f32_32x32x16_bf16 v[114:129], v[194:197], v[182:185], v[114:129]
	s_waitcnt lgkmcnt(10)
	v_mfma_f32_32x32x16_bf16 v[98:113], v[134:137], v[182:185], v[98:113]
	v_add_f32_e32 v66, v72, v94
	v_add_f32_e32 v66, v73, v66
	v_add_f32_e32 v66, v74, v66
	v_add_f32_e32 v66, v75, v66
	v_cvt_pk_bf16_f32 v168, v70, v71
	v_cvt_pk_bf16_f32 v169, v72, v73
	s_nop 0
	v_add_f32_e32 v66, v76, v66
	v_add_f32_e32 v66, v77, v66
	v_add_f32_e32 v66, v78, v66
	v_add_f32_e32 v66, v79, v66
	v_cvt_pk_bf16_f32 v162, v74, v75
	v_cvt_pk_bf16_f32 v163, v76, v77
	s_waitcnt lgkmcnt(9)
	v_mfma_f32_32x32x16_bf16 v[114:129], v[138:141], v[178:181], v[114:129]
	s_waitcnt lgkmcnt(8)
	v_mfma_f32_32x32x16_bf16 v[98:113], v[130:133], v[178:181], v[98:113]
	v_add_f32_e32 v66, v80, v66
	v_add_f32_e32 v66, v81, v66
	v_add_f32_e32 v66, 0, v66
	v_cvt_pk_bf16_f32 v164, v78, v79
	v_cvt_pk_bf16_f32 v165, v80, v81
	s_lshl_b32 s12, s7, 13
	s_add_i32 s12, s12, s91
	v_add_f32_e32 v198, v202, v66
	v_lshl_add_u64 v[66:67], v[146:147], 0, s[24:25]
	s_mov_b32 s13, m0
	s_mov_b32 m0, s12
	s_nop 0
	global_load_lds_dwordx4 v[66:67], off
	s_mov_b32 m0, s13
	s_lshl_b32 s12, s0, 14
	v_lshl_add_u64 v[66:67], v[148:149], 0, s[4:5]
	s_add_i32 s12, s12, s92
	s_mov_b32 s13, m0
	s_mov_b32 m0, s12
	s_nop 0
	global_load_lds_dwordx4 v[66:67], off
	s_mov_b32 m0, s13
	v_lshl_add_u64 v[66:67], v[148:149], 0, s[8:9]
	s_addk_i32 s12, 0x2000
	s_mov_b32 s13, m0
	s_mov_b32 m0, s12
	s_nop 0
	global_load_lds_dwordx4 v[66:67], off
	s_mov_b32 m0, s13
	s_waitcnt lgkmcnt(6)
	v_mfma_f32_32x32x16_bf16 v[50:65], v[174:177], v[150:153], v[50:65]
	v_exp_f32_e32 v114, v114
	v_exp_f32_e32 v115, v115
	ds_read_b64_tr_b16 v[66:67], v154 offset:25600
	ds_read_b64_tr_b16 v[68:69], v154 offset:26112
	s_waitcnt lgkmcnt(6)
	v_mfma_f32_32x32x16_bf16 v[34:49], v[174:177], v[82:85], v[34:49]
	v_exp_f32_e32 v116, v116
	v_exp_f32_e32 v117, v117
	ds_read_b64_tr_b16 v[70:71], v154 offset:29696
	ds_read_b64_tr_b16 v[72:73], v154 offset:30208
	s_waitcnt lgkmcnt(6)
	v_mfma_f32_32x32x16_bf16 v[18:33], v[174:177], v[86:89], v[18:33]
	v_exp_f32_e32 v118, v118
	v_exp_f32_e32 v119, v119
	ds_read_b64_tr_b16 v[74:75], v154 offset:33792
	ds_read_b64_tr_b16 v[76:77], v154 offset:34304
	s_waitcnt lgkmcnt(6)
	v_mfma_f32_32x32x16_bf16 v[2:17], v[174:177], v[90:93], v[2:17]
	v_exp_f32_e32 v120, v120
	v_exp_f32_e32 v121, v121
	ds_read_b64_tr_b16 v[78:79], v154 offset:37888
	ds_read_b64_tr_b16 v[80:81], v154 offset:38400
	s_waitcnt lgkmcnt(6)
	v_mfma_f32_32x32x16_bf16 v[50:65], v[170:173], v[66:69], v[50:65]
	v_exp_f32_e32 v122, v122
	v_exp_f32_e32 v123, v123
	ds_read_b64_tr_b16 v[82:83], v154 offset:26624
	ds_read_b64_tr_b16 v[84:85], v154 offset:27136
	s_waitcnt lgkmcnt(6)
	v_mfma_f32_32x32x16_bf16 v[34:49], v[170:173], v[70:73], v[34:49]
	v_exp_f32_e32 v124, v124
	v_exp_f32_e32 v125, v125
	ds_read_b64_tr_b16 v[66:67], v154 offset:30720
	ds_read_b64_tr_b16 v[68:69], v154 offset:31232
	s_waitcnt lgkmcnt(6)
	v_mfma_f32_32x32x16_bf16 v[18:33], v[170:173], v[74:77], v[18:33]
	s_lshl_b32 s60, s0, 13
	v_exp_f32_e32 v126, v126
	v_exp_f32_e32 v127, v127
	v_add_u32_e32 v90, s60, v243
	ds_read_b128 v[70:73], v90
	ds_read_b128 v[130:133], v90 offset:512
	ds_read_b64_tr_b16 v[86:87], v154 offset:34816
	ds_read_b64_tr_b16 v[88:89], v154 offset:35328
	s_waitcnt lgkmcnt(8)
	v_mfma_f32_32x32x16_bf16 v[2:17], v[170:173], v[78:81], v[2:17]
	v_exp_f32_e32 v128, v128
	v_exp_f32_e32 v129, v129
	ds_read_b64_tr_b16 v[74:75], v154 offset:38912
	ds_read_b64_tr_b16 v[76:77], v154 offset:39424
	s_waitcnt lgkmcnt(8)
	v_mfma_f32_32x32x16_bf16 v[50:65], v[166:169], v[82:85], v[50:65]
	v_exp_f32_e32 v98, v98
	v_exp_f32_e32 v99, v99
	ds_read_b128 v[134:137], v90 offset:2048
	ds_read_b128 v[138:141], v90 offset:2560
	ds_read_b64_tr_b16 v[78:79], v154 offset:27648
	ds_read_b64_tr_b16 v[80:81], v154 offset:28160
	s_waitcnt lgkmcnt(10)
	v_mfma_f32_32x32x16_bf16 v[34:49], v[166:169], v[66:69], v[34:49]
	v_exp_f32_e32 v100, v100
	v_exp_f32_e32 v101, v101
	ds_read_b64_tr_b16 v[82:83], v154 offset:31744
	ds_read_b64_tr_b16 v[84:85], v154 offset:32256
	s_waitcnt lgkmcnt(8)
	v_mfma_f32_32x32x16_bf16 v[18:33], v[166:169], v[86:89], v[18:33]
	v_exp_f32_e32 v102, v102
	v_exp_f32_e32 v103, v103
	ds_read_b128 v[142:145], v90 offset:4096
	ds_read_b128 v[150:153], v90 offset:4608
	ds_read_b64_tr_b16 v[66:67], v154 offset:35840
	ds_read_b64_tr_b16 v[68:69], v154 offset:36352
	s_waitcnt lgkmcnt(10)
	v_mfma_f32_32x32x16_bf16 v[2:17], v[166:169], v[74:77], v[2:17]
	v_exp_f32_e32 v104, v104
	v_exp_f32_e32 v105, v105
	ds_read_b64_tr_b16 v[86:87], v154 offset:39936
	ds_read_b64_tr_b16 v[88:89], v154 offset:40448
	s_waitcnt lgkmcnt(8)
	v_mfma_f32_32x32x16_bf16 v[50:65], v[162:165], v[78:81], v[50:65]
	ds_read_b128 v[154:157], v90 offset:6144
	ds_read_b128 v[158:161], v90 offset:6656
	v_exp_f32_e32 v106, v106
	v_exp_f32_e32 v107, v107
	s_cmp_lg_u32 s98, 0
	s_cbranch_scc0 .Lst_e0
	s_waitcnt vmcnt(3) lgkmcnt(0)
	s_barrier
.Lst_e0:
	s_waitcnt lgkmcnt(8)
	v_mfma_f32_32x32x16_bf16 v[34:49], v[162:165], v[82:85], v[34:49]
	v_exp_f32_e32 v108, v108
	v_exp_f32_e32 v109, v109
	s_waitcnt lgkmcnt(4)
	v_mfma_f32_32x32x16_bf16 v[18:33], v[162:165], v[66:69], v[18:33]
	v_exp_f32_e32 v110, v110
	v_exp_f32_e32 v111, v111
	s_waitcnt lgkmcnt(2)
	v_mfma_f32_32x32x16_bf16 v[2:17], v[162:165], v[86:89], v[2:17]
	v_exp_f32_e32 v112, v112
	v_exp_f32_e32 v113, v113
	s_cmp_lg_u32 s98, 0
	s_cbranch_scc1 .Lst_b0
	s_waitcnt vmcnt(3) lgkmcnt(0)
	s_barrier
.Lst_b0:
	s_add_i32 s12, s0, 1
	s_cmp_lg_u32 s0, 2
	s_cselect_b32 s33, s12, 0
	v_lshl_add_u32 v244, s7, 14, v241
	ds_read_b64_tr_b16 v[194:195], v244 offset:24576
	ds_read_b64_tr_b16 v[196:197], v244 offset:25088
	v_mfma_f32_32x32x16_bf16 v[82:97], v[70:73], v[190:193], 0
	v_add_f32_e32 v66, v114, v115
	v_add_f32_e32 v66, v116, v66
	v_add_f32_e32 v66, v117, v66
	v_add_f32_e32 v66, v118, v66
	v_add_f32_e32 v66, v119, v66
	v_cvt_pk_bf16_f32 v174, v114, v115
	v_cvt_pk_bf16_f32 v175, v116, v117
	ds_read_b64_tr_b16 v[114:115], v244 offset:28672
	ds_read_b64_tr_b16 v[116:117], v244 offset:29184
	v_add_f32_e32 v66, v120, v66
	v_add_f32_e32 v66, v121, v66
	v_add_f32_e32 v66, v122, v66
	v_add_f32_e32 v162, v123, v66
	v_mfma_f32_32x32x16_bf16 v[66:81], v[130:133], v[190:193], 0
	v_cvt_pk_bf16_f32 v176, v118, v119
	v_cvt_pk_bf16_f32 v177, v120, v121
	ds_read_b64_tr_b16 v[118:119], v244 offset:32768
	ds_read_b64_tr_b16 v[120:121], v244 offset:33280
	v_mfma_f32_32x32x16_bf16 v[82:97], v[134:137], v[186:189], v[82:97]
	v_add_f32_e32 v130, v124, v162
	v_add_f32_e32 v130, v125, v130
	v_add_f32_e32 v130, v126, v130
	v_add_f32_e32 v130, v127, v130
	v_cvt_pk_bf16_f32 v170, v122, v123
	v_cvt_pk_bf16_f32 v171, v124, v125
	ds_read_b64_tr_b16 v[122:123], v244 offset:36864
	ds_read_b64_tr_b16 v[124:125], v244 offset:37376
	v_mfma_f32_32x32x16_bf16 v[66:81], v[138:141], v[186:189], v[66:81]
	v_add_f32_e32 v130, v128, v130
	v_add_f32_e32 v130, v129, v130
	v_add_f32_e32 v130, v98, v130
	v_add_f32_e32 v130, v99, v130
	v_cvt_pk_bf16_f32 v172, v126, v127
	v_cvt_pk_bf16_f32 v173, v128, v129
	v_mfma_f32_32x32x16_bf16 v[82:97], v[142:145], v[182:185], v[82:97]
	v_add_f32_e32 v126, v100, v130
	v_add_f32_e32 v126, v101, v126
	v_add_f32_e32 v126, v102, v126
	v_add_f32_e32 v126, v103, v126
	v_cvt_pk_bf16_f32 v166, v98, v99
	v_cvt_pk_bf16_f32 v167, v100, v101
	v_mfma_f32_32x32x16_bf16 v[66:81], v[150:153], v[182:185], v[66:81]
	v_add_f32_e32 v98, v104, v126
	v_add_f32_e32 v98, v105, v98
	v_add_f32_e32 v98, v106, v98
	v_add_f32_e32 v98, v107, v98
	v_cvt_pk_bf16_f32 v168, v102, v103
	v_cvt_pk_bf16_f32 v169, v104, v105
	s_waitcnt lgkmcnt(9)
	v_mfma_f32_32x32x16_bf16 v[82:97], v[154:157], v[178:181], v[82:97]
	v_add_f32_e32 v98, v108, v98
	v_add_f32_e32 v98, v109, v98
	v_add_f32_e32 v98, v110, v98
	v_add_f32_e32 v98, v111, v98
	v_cvt_pk_bf16_f32 v162, v106, v107
	v_cvt_pk_bf16_f32 v163, v108, v109
	s_waitcnt lgkmcnt(8)
	v_mfma_f32_32x32x16_bf16 v[66:81], v[158:161], v[178:181], v[66:81]
	v_add_f32_e32 v98, v112, v98
	v_add_f32_e32 v98, v113, v98
	v_add_f32_e32 v98, 0, v98
	v_cvt_pk_bf16_f32 v164, v110, v111
	v_cvt_pk_bf16_f32 v165, v112, v113
	s_add_i32 s7, s60, s91
	v_add_f32_e32 v202, v198, v98
	v_lshl_add_u64 v[98:99], v[146:147], 0, s[30:31]
	s_mov_b32 s12, m0
	s_mov_b32 m0, s7
	s_nop 0
	global_load_lds_dwordx4 v[98:99], off
	s_mov_b32 m0, s12
	s_lshl_b32 s7, s33, 14
	v_lshl_add_u64 v[106:107], v[148:149], 0, s[22:23]
	s_add_i32 s7, s7, s92
	s_mov_b32 s12, m0
	s_mov_b32 m0, s7
	s_nop 0
	global_load_lds_dwordx4 v[106:107], off
	s_mov_b32 m0, s12
	v_lshl_add_u64 v[98:99], v[148:149], 0, s[44:45]
	s_addk_i32 s7, 0x2000
	s_mov_b32 s12, m0
	s_mov_b32 m0, s7
	s_nop 0
	global_load_lds_dwordx4 v[98:99], off
	s_mov_b32 m0, s12
	s_waitcnt lgkmcnt(6)
	v_mfma_f32_32x32x16_bf16 v[50:65], v[174:177], v[194:197], v[50:65]
	v_exp_f32_e32 v82, v82
	v_exp_f32_e32 v83, v83
	ds_read_b64_tr_b16 v[98:99], v244 offset:25600
	ds_read_b64_tr_b16 v[100:101], v244 offset:26112
	s_waitcnt lgkmcnt(6)
	v_mfma_f32_32x32x16_bf16 v[34:49], v[174:177], v[114:117], v[34:49]
	v_exp_f32_e32 v84, v84
	v_exp_f32_e32 v85, v85
	ds_read_b64_tr_b16 v[102:103], v244 offset:29696
	ds_read_b64_tr_b16 v[104:105], v244 offset:30208
	s_waitcnt lgkmcnt(6)
	v_mfma_f32_32x32x16_bf16 v[18:33], v[174:177], v[118:121], v[18:33]
	v_exp_f32_e32 v86, v86
	v_exp_f32_e32 v87, v87
	ds_read_b64_tr_b16 v[108:109], v244 offset:33792
	ds_read_b64_tr_b16 v[110:111], v244 offset:34304
	s_waitcnt lgkmcnt(6)
	v_mfma_f32_32x32x16_bf16 v[2:17], v[174:177], v[122:125], v[2:17]
	v_exp_f32_e32 v88, v88
	v_exp_f32_e32 v89, v89
	ds_read_b64_tr_b16 v[112:113], v244 offset:37888
	ds_read_b64_tr_b16 v[114:115], v244 offset:38400
	s_waitcnt lgkmcnt(6)
	v_mfma_f32_32x32x16_bf16 v[50:65], v[170:173], v[98:101], v[50:65]
	v_exp_f32_e32 v90, v90
	v_exp_f32_e32 v91, v91
	ds_read_b64_tr_b16 v[116:117], v244 offset:26624
	ds_read_b64_tr_b16 v[118:119], v244 offset:27136
	s_waitcnt lgkmcnt(6)
	v_mfma_f32_32x32x16_bf16 v[34:49], v[170:173], v[102:105], v[34:49]
	v_exp_f32_e32 v92, v92
	v_exp_f32_e32 v93, v93
	ds_read_b64_tr_b16 v[120:121], v244 offset:30720
	ds_read_b64_tr_b16 v[122:123], v244 offset:31232
	s_waitcnt lgkmcnt(6)
	v_mfma_f32_32x32x16_bf16 v[18:33], v[170:173], v[108:111], v[18:33]
	v_exp_f32_e32 v94, v94
	v_exp_f32_e32 v95, v95
	v_lshl_add_u32 v128, s33, 13, v243
	ds_read_b128 v[102:105], v128
	ds_read_b128 v[98:101], v128 offset:512
	ds_read_b64_tr_b16 v[124:125], v244 offset:34816
	ds_read_b64_tr_b16 v[126:127], v244 offset:35328
	s_waitcnt lgkmcnt(8)
; #define ATT_WAIT_BAR(N) asm volatile("s_waitcnt vmcnt(" #N ") lgkmcnt(0)\n\ts_barrier" ::: "memory")
; #define ROT() do { sl_prev = sl_cur; sl_cur = sl_next; sl_next = (sl_next == 2) ? 0 : sl_next + 1; } while (0)
; __device__ __forceinline__ void attn_unit(int b, int h, int qb, bool first, bool has_next, int nb, int nh, bf16_t* QO, const bf16_t* __restrict__ K, const bf16_t* __restrict__ V, float lam, char* shm) {
;     ...
;         int t = 1;
; #pragma unroll 1
;         for (; t + 1 <= NT - 4; t += 2) {
;             STEP(pB0, pB1, pA0, pA1, t, true, true, true);     ATT_WAIT_BAR(3); ROT();
;             STEP(pA0, pA1, pB0, pB1, t + 1, true, true, true); ATT_WAIT_BAR(3); ROT();
;         }
;         STEP(pB0, pB1, pA0, pA1, NT - 3, false, true, true);   ATT_WAIT_BAR(2); ROT();
	v_mfma_f32_32x32x16_bf16 v[2:17], v[170:173], v[112:115], v[2:17]
	v_exp_f32_e32 v96, v96
	v_exp_f32_e32 v97, v97
	ds_read_b64_tr_b16 v[108:109], v244 offset:38912
	ds_read_b64_tr_b16 v[110:111], v244 offset:39424
	s_waitcnt lgkmcnt(8)
	v_mfma_f32_32x32x16_bf16 v[50:65], v[166:169], v[116:119], v[50:65]
	v_exp_f32_e32 v66, v66
	v_exp_f32_e32 v67, v67
	ds_read_b128 v[198:201], v128 offset:2048
	ds_read_b128 v[142:145], v128 offset:2560
	ds_read_b64_tr_b16 v[112:113], v244 offset:27648
	ds_read_b64_tr_b16 v[114:115], v244 offset:28160
	s_waitcnt lgkmcnt(10)
	v_mfma_f32_32x32x16_bf16 v[34:49], v[166:169], v[120:123], v[34:49]
	v_exp_f32_e32 v68, v68
	v_exp_f32_e32 v69, v69
	ds_read_b64_tr_b16 v[116:117], v244 offset:31744
	ds_read_b64_tr_b16 v[118:119], v244 offset:32256
	s_waitcnt lgkmcnt(8)
	v_mfma_f32_32x32x16_bf16 v[18:33], v[166:169], v[124:127], v[18:33]
	v_exp_f32_e32 v70, v70
	v_exp_f32_e32 v71, v71
	ds_read_b128 v[194:197], v128 offset:4096
	ds_read_b128 v[134:137], v128 offset:4608
	ds_read_b64_tr_b16 v[120:121], v244 offset:35840
	ds_read_b64_tr_b16 v[122:123], v244 offset:36352
	s_waitcnt lgkmcnt(10)
	v_mfma_f32_32x32x16_bf16 v[2:17], v[166:169], v[108:111], v[2:17]
	v_exp_f32_e32 v72, v72
	v_exp_f32_e32 v73, v73
	ds_read_b64_tr_b16 v[124:125], v244 offset:39936
	ds_read_b64_tr_b16 v[126:127], v244 offset:40448
	s_waitcnt lgkmcnt(8)
	v_mfma_f32_32x32x16_bf16 v[50:65], v[162:165], v[112:115], v[50:65]
	ds_read_b128 v[138:141], v128 offset:6144
	ds_read_b128 v[130:133], v128 offset:6656
	v_exp_f32_e32 v74, v74
	v_exp_f32_e32 v75, v75
	s_cmp_lg_u32 s98, 0
	s_cbranch_scc0 .Lst_e1
	s_waitcnt vmcnt(3) lgkmcnt(0)
	s_barrier
.Lst_e1:
	s_waitcnt lgkmcnt(8)
	v_mfma_f32_32x32x16_bf16 v[34:49], v[162:165], v[116:119], v[34:49]
	v_exp_f32_e32 v76, v76
	v_exp_f32_e32 v77, v77
	s_waitcnt lgkmcnt(4)
	v_mfma_f32_32x32x16_bf16 v[18:33], v[162:165], v[120:123], v[18:33]
	v_exp_f32_e32 v78, v78
	v_exp_f32_e32 v79, v79
	s_waitcnt lgkmcnt(2)
	v_mfma_f32_32x32x16_bf16 v[2:17], v[162:165], v[124:127], v[2:17]
	v_exp_f32_e32 v80, v80
	v_exp_f32_e32 v81, v81
	s_add_i32 s12, s33, 1
	s_cmp_lg_u32 s98, 0
	s_cbranch_scc1 .Lst_b1
	s_waitcnt vmcnt(3) lgkmcnt(0)
	s_barrier
.Lst_b1:
	s_cmp_lg_u32 s33, 2
	s_mov_b32 s60, s0
	s_cselect_b32 s0, s12, 0
	s_add_i32 s6, s6, 2
	v_lshl_add_u64 v[146:147], v[146:147], 0, s[22:23]
	v_mov_b64_e32 v[148:149], v[106:107]
	s_mov_b32 s7, s33
	s_cmp_lt_u32 s6, 26
	s_cbranch_scc1 .LBB0_375
	ds_read_b64_tr_b16 v[106:107], v241 offset:40960
	ds_read_b64_tr_b16 v[108:109], v241 offset:41472
	v_add_f32_e32 v110, v82, v83
	v_add_f32_e32 v110, v84, v110
	v_add_f32_e32 v110, v85, v110
	v_add_f32_e32 v110, v86, v110
	v_add_f32_e32 v110, v87, v110
	v_cvt_pk_bf16_f32 v174, v82, v83
	v_cvt_pk_bf16_f32 v175, v84, v85
	v_mfma_f32_32x32x16_bf16 v[146:161], v[102:105], v[190:193], 0
	ds_read_b64_tr_b16 v[82:83], v241 offset:45056
	ds_read_b64_tr_b16 v[84:85], v241 offset:45568
	v_mfma_f32_32x32x16_bf16 v[114:129], v[98:101], v[190:193], 0
	v_add_f32_e32 v102, v88, v110
	v_add_f32_e32 v102, v89, v102
	v_add_f32_e32 v102, v90, v102
	v_add_f32_e32 v102, v91, v102
	v_cvt_pk_bf16_f32 v176, v86, v87
	v_cvt_pk_bf16_f32 v177, v88, v89
	ds_read_b64_tr_b16 v[86:87], v241 offset:49152
	ds_read_b64_tr_b16 v[88:89], v241 offset:49664
	v_add_f32_e32 v98, v92, v102
	v_add_f32_e32 v98, v93, v98
	v_add_f32_e32 v98, v94, v98
	v_add_f32_e32 v98, v95, v98
	v_cvt_pk_bf16_f32 v170, v90, v91
	v_cvt_pk_bf16_f32 v171, v92, v93
	v_mfma_f32_32x32x16_bf16 v[146:161], v[198:201], v[186:189], v[146:161]
	ds_read_b64_tr_b16 v[90:91], v241 offset:53248
	ds_read_b64_tr_b16 v[92:93], v241 offset:53760
	v_mfma_f32_32x32x16_bf16 v[114:129], v[142:145], v[186:189], v[114:129]
	v_add_f32_e32 v98, v96, v98
	v_add_f32_e32 v98, v97, v98
	v_add_f32_e32 v98, v66, v98
	v_add_f32_e32 v98, v67, v98
	v_cvt_pk_bf16_f32 v172, v94, v95
	v_cvt_pk_bf16_f32 v173, v96, v97
	s_nop 0
	v_add_f32_e32 v94, v68, v98
	v_add_f32_e32 v94, v69, v94
	v_add_f32_e32 v94, v70, v94
	v_add_f32_e32 v94, v71, v94
	v_cvt_pk_bf16_f32 v166, v66, v67
	v_cvt_pk_bf16_f32 v167, v68, v69
	v_mfma_f32_32x32x16_bf16 v[146:161], v[194:197], v[182:185], v[146:161]
	v_mfma_f32_32x32x16_bf16 v[114:129], v[134:137], v[182:185], v[114:129]
	v_add_f32_e32 v66, v72, v94
	v_add_f32_e32 v66, v73, v66
	v_add_f32_e32 v66, v74, v66
	v_add_f32_e32 v66, v75, v66
	v_cvt_pk_bf16_f32 v168, v70, v71
	v_cvt_pk_bf16_f32 v169, v72, v73
	s_nop 0
	v_add_f32_e32 v66, v76, v66
	v_add_f32_e32 v66, v77, v66
	v_add_f32_e32 v66, v78, v66
	v_add_f32_e32 v66, v79, v66
	v_cvt_pk_bf16_f32 v162, v74, v75
	v_cvt_pk_bf16_f32 v163, v76, v77
	s_waitcnt lgkmcnt(9)
	v_mfma_f32_32x32x16_bf16 v[146:161], v[138:141], v[178:181], v[146:161]
	s_waitcnt lgkmcnt(8)
	v_mfma_f32_32x32x16_bf16 v[114:129], v[130:133], v[178:181], v[114:129]
	v_add_f32_e32 v66, v80, v66
	v_add_f32_e32 v66, v81, v66
	v_add_f32_e32 v194, 0, v66
	v_cvt_pk_bf16_f32 v164, v78, v79
	v_cvt_pk_bf16_f32 v165, v80, v81
	s_mov_b32 s0, m0
	s_mov_b32 m0, s92
	s_nop 0
	global_load_lds_dwordx4 v[214:215], off
	s_mov_b32 m0, s0
	s_add_i32 s0, s92, 0x2000
	s_mov_b32 s6, m0
	s_mov_b32 m0, s0
	s_nop 0
	global_load_lds_dwordx4 v[216:217], off
	s_mov_b32 m0, s6
	s_waitcnt lgkmcnt(6)
	v_mfma_f32_32x32x16_bf16 v[50:65], v[174:177], v[106:109], v[50:65]
	s_nop 1
	v_exp_f32_e32 v146, v146
	v_exp_f32_e32 v147, v147
	ds_read_b64_tr_b16 v[66:67], v241 offset:41984
	ds_read_b64_tr_b16 v[68:69], v241 offset:42496
	s_waitcnt lgkmcnt(6)
	v_mfma_f32_32x32x16_bf16 v[34:49], v[174:177], v[82:85], v[34:49]
	v_exp_f32_e32 v148, v148
	v_exp_f32_e32 v149, v149
	ds_read_b64_tr_b16 v[70:71], v241 offset:46080
	ds_read_b64_tr_b16 v[72:73], v241 offset:46592
	s_waitcnt lgkmcnt(6)
; #define ATT_WAIT_BAR(N) asm volatile("s_waitcnt vmcnt(" #N ") lgkmcnt(0)\n\ts_barrier" ::: "memory")
; #define ROT() do { sl_prev = sl_cur; sl_cur = sl_next; sl_next = (sl_next == 2) ? 0 : sl_next + 1; } while (0)
; __device__ __forceinline__ void attn_unit(int b, int h, int qb, bool first, bool has_next, int nb, int nh, bf16_t* QO, const bf16_t* __restrict__ K, const bf16_t* __restrict__ V, float lam, char* shm) {
;     ...
;         int t = 1;
; #pragma unroll 1
;         for (; t + 1 <= NT - 4; t += 2) {
;             STEP(pB0, pB1, pA0, pA1, t, true, true, true);     ATT_WAIT_BAR(3); ROT();
;             STEP(pA0, pA1, pB0, pB1, t + 1, true, true, true); ATT_WAIT_BAR(3); ROT();
;         }
;         STEP(pB0, pB1, pA0, pA1, NT - 3, false, true, true);   ATT_WAIT_BAR(2); ROT();
;         STEP(pA0, pA1, pB0, pB1, NT - 2, false, true, true);   ATT_WAIT_BAR(0); ROT();
	v_mfma_f32_32x32x16_bf16 v[18:33], v[174:177], v[86:89], v[18:33]
	v_exp_f32_e32 v150, v150
	v_exp_f32_e32 v151, v151
	ds_read_b64_tr_b16 v[74:75], v241 offset:50176
	ds_read_b64_tr_b16 v[76:77], v241 offset:50688
	s_waitcnt lgkmcnt(6)
	v_mfma_f32_32x32x16_bf16 v[2:17], v[174:177], v[90:93], v[2:17]
	v_exp_f32_e32 v152, v152
	v_exp_f32_e32 v153, v153
	ds_read_b64_tr_b16 v[78:79], v241 offset:54272
	ds_read_b64_tr_b16 v[80:81], v241 offset:54784
	s_waitcnt lgkmcnt(6)
	v_mfma_f32_32x32x16_bf16 v[50:65], v[170:173], v[66:69], v[50:65]
	v_exp_f32_e32 v154, v154
	v_exp_f32_e32 v155, v155
	ds_read_b64_tr_b16 v[82:83], v241 offset:43008
	ds_read_b64_tr_b16 v[84:85], v241 offset:43520
	s_waitcnt lgkmcnt(6)
	v_mfma_f32_32x32x16_bf16 v[34:49], v[170:173], v[70:73], v[34:49]
	v_exp_f32_e32 v156, v156
	v_exp_f32_e32 v157, v157
	ds_read_b64_tr_b16 v[66:67], v241 offset:47104
	ds_read_b64_tr_b16 v[68:69], v241 offset:47616
	s_waitcnt lgkmcnt(6)
	v_mfma_f32_32x32x16_bf16 v[18:33], v[170:173], v[74:77], v[18:33]
	v_exp_f32_e32 v158, v158
	v_exp_f32_e32 v159, v159
	ds_read_b128 v[70:73], v243
	ds_read_b128 v[86:89], v243 offset:512
	ds_read_b64_tr_b16 v[90:91], v241 offset:51200
	ds_read_b64_tr_b16 v[92:93], v241 offset:51712
	s_waitcnt lgkmcnt(8)
	v_mfma_f32_32x32x16_bf16 v[2:17], v[170:173], v[78:81], v[2:17]
	v_exp_f32_e32 v160, v160
	v_exp_f32_e32 v161, v161
	ds_read_b64_tr_b16 v[74:75], v241 offset:55296
	ds_read_b64_tr_b16 v[76:77], v241 offset:55808
	s_waitcnt lgkmcnt(8)
	v_mfma_f32_32x32x16_bf16 v[50:65], v[166:169], v[82:85], v[50:65]
	v_exp_f32_e32 v114, v114
	v_exp_f32_e32 v115, v115
	ds_read_b128 v[78:81], v243 offset:2048
	ds_read_b128 v[94:97], v243 offset:2560
	ds_read_b64_tr_b16 v[98:99], v241 offset:44032
	ds_read_b64_tr_b16 v[100:101], v241 offset:44544
	s_waitcnt lgkmcnt(10)
	v_mfma_f32_32x32x16_bf16 v[34:49], v[166:169], v[66:69], v[34:49]
	v_exp_f32_e32 v116, v116
	v_exp_f32_e32 v117, v117
	ds_read_b64_tr_b16 v[82:83], v241 offset:48128
	ds_read_b64_tr_b16 v[84:85], v241 offset:48640
	s_waitcnt lgkmcnt(8)
	v_mfma_f32_32x32x16_bf16 v[18:33], v[166:169], v[90:93], v[18:33]
	v_exp_f32_e32 v118, v118
	v_exp_f32_e32 v119, v119
	ds_read_b128 v[66:69], v243 offset:4096
	ds_read_b128 v[196:199], v243 offset:4608
	ds_read_b64_tr_b16 v[102:103], v241 offset:52224
	ds_read_b64_tr_b16 v[104:105], v241 offset:52736
	s_waitcnt lgkmcnt(10)
	v_mfma_f32_32x32x16_bf16 v[2:17], v[166:169], v[74:77], v[2:17]
	v_exp_f32_e32 v120, v120
	v_exp_f32_e32 v121, v121
	ds_read_b64_tr_b16 v[90:91], v241 offset:56320
	ds_read_b64_tr_b16 v[92:93], v241 offset:56832
	s_waitcnt lgkmcnt(8)
	v_mfma_f32_32x32x16_bf16 v[50:65], v[162:165], v[98:101], v[50:65]
	ds_read_b128 v[74:77], v243 offset:6144
	ds_read_b128 v[244:247], v243 offset:6656
	v_exp_f32_e32 v122, v122
	v_exp_f32_e32 v123, v123
	s_waitcnt lgkmcnt(8)
	v_mfma_f32_32x32x16_bf16 v[34:49], v[162:165], v[82:85], v[34:49]
	v_exp_f32_e32 v124, v124
	v_exp_f32_e32 v125, v125
	s_waitcnt lgkmcnt(4)
	v_mfma_f32_32x32x16_bf16 v[18:33], v[162:165], v[102:105], v[18:33]
	v_exp_f32_e32 v126, v126
	v_exp_f32_e32 v127, v127
	s_waitcnt lgkmcnt(2)
	v_mfma_f32_32x32x16_bf16 v[2:17], v[162:165], v[90:93], v[2:17]
	v_exp_f32_e32 v128, v128
	v_exp_f32_e32 v129, v129
	s_waitcnt vmcnt(2) lgkmcnt(0)
	s_barrier
	ds_read_b64_tr_b16 v[82:83], v241 offset:57344
	ds_read_b64_tr_b16 v[84:85], v241 offset:57856
	v_add_f32_e32 v90, v146, v147
	v_add_f32_e32 v90, v148, v90
	v_add_f32_e32 v90, v149, v90
	v_add_f32_e32 v90, v150, v90
	v_add_f32_e32 v90, v151, v90
	v_cvt_pk_bf16_f32 v174, v146, v147
	v_cvt_pk_bf16_f32 v175, v148, v149
	v_mfma_f32_32x32x16_bf16 v[130:145], v[70:73], v[190:193], 0
	ds_read_b64_tr_b16 v[70:71], v241 offset:61440
	ds_read_b64_tr_b16 v[72:73], v241 offset:61952
	v_mfma_f32_32x32x16_bf16 v[98:113], v[86:89], v[190:193], 0
	v_add_f32_e32 v90, v152, v90
	v_add_f32_e32 v90, v153, v90
	v_add_f32_e32 v90, v154, v90
	v_add_f32_e32 v90, v155, v90
	v_cvt_pk_bf16_f32 v176, v150, v151
	v_cvt_pk_bf16_f32 v177, v152, v153
	ds_read_b64_tr_b16 v[86:87], v242 offset:40960
	ds_read_b64_tr_b16 v[88:89], v242 offset:41472
	v_add_f32_e32 v90, v156, v90
	v_add_f32_e32 v90, v157, v90
	v_add_f32_e32 v90, v158, v90
	v_add_f32_e32 v90, v159, v90
	v_cvt_pk_bf16_f32 v170, v154, v155
	v_cvt_pk_bf16_f32 v171, v156, v157
	v_mfma_f32_32x32x16_bf16 v[130:145], v[78:81], v[186:189], v[130:145]
	ds_read_b64_tr_b16 v[78:79], v242 offset:45056
	ds_read_b64_tr_b16 v[80:81], v242 offset:45568
	v_mfma_f32_32x32x16_bf16 v[98:113], v[94:97], v[186:189], v[98:113]
	v_add_f32_e32 v90, v160, v90
	v_add_f32_e32 v90, v161, v90
	v_add_f32_e32 v90, v114, v90
	v_add_f32_e32 v90, v115, v90
	v_cvt_pk_bf16_f32 v172, v158, v159
	v_cvt_pk_bf16_f32 v173, v160, v161
	s_nop 0
	v_add_f32_e32 v90, v116, v90
	v_add_f32_e32 v90, v117, v90
	v_add_f32_e32 v90, v118, v90
	v_add_f32_e32 v90, v119, v90
	v_cvt_pk_bf16_f32 v166, v114, v115
	v_cvt_pk_bf16_f32 v167, v116, v117
	v_mfma_f32_32x32x16_bf16 v[130:145], v[66:69], v[182:185], v[130:145]
	v_mfma_f32_32x32x16_bf16 v[98:113], v[196:199], v[182:185], v[98:113]
	v_add_f32_e32 v66, v120, v90
	v_add_f32_e32 v66, v121, v66
	v_add_f32_e32 v66, v122, v66
	v_add_f32_e32 v66, v123, v66
	v_cvt_pk_bf16_f32 v168, v118, v119
	v_cvt_pk_bf16_f32 v169, v120, v121
	s_nop 0
	v_add_f32_e32 v66, v124, v66
	v_add_f32_e32 v66, v125, v66
	v_add_f32_e32 v66, v126, v66
	v_add_f32_e32 v66, v127, v66
	v_cvt_pk_bf16_f32 v162, v122, v123
	v_cvt_pk_bf16_f32 v163, v124, v125
	s_waitcnt lgkmcnt(9)
	v_mfma_f32_32x32x16_bf16 v[130:145], v[74:77], v[178:181], v[130:145]
	s_waitcnt lgkmcnt(8)
; #define ATT_WAIT_BAR(N) asm volatile("s_waitcnt vmcnt(" #N ") lgkmcnt(0)\n\ts_barrier" ::: "memory")
; #define ROT() do { sl_prev = sl_cur; sl_cur = sl_next; sl_next = (sl_next == 2) ? 0 : sl_next + 1; } while (0)
; __device__ __forceinline__ void attn_unit(int b, int h, int qb, bool first, bool has_next, int nb, int nh, bf16_t* QO, const bf16_t* __restrict__ K, const bf16_t* __restrict__ V, float lam, char* shm) {
;     ...
;         int t = 1;
; #pragma unroll 1
;         for (; t + 1 <= NT - 4; t += 2) {
;             STEP(pB0, pB1, pA0, pA1, t, true, true, true);     ATT_WAIT_BAR(3); ROT();
;             STEP(pA0, pA1, pB0, pB1, t + 1, true, true, true); ATT_WAIT_BAR(3); ROT();
;         }
;         STEP(pB0, pB1, pA0, pA1, NT - 3, false, true, true);   ATT_WAIT_BAR(2); ROT();
;         STEP(pA0, pA1, pB0, pB1, NT - 2, false, true, true);   ATT_WAIT_BAR(0); ROT();
	v_mfma_f32_32x32x16_bf16 v[98:113], v[244:247], v[178:181], v[98:113]
	v_add_f32_e32 v66, v128, v66
	v_add_f32_e32 v66, v129, v66
	v_add_f32_e32 v114, 0, v66
	v_cvt_pk_bf16_f32 v164, v126, v127
	v_cvt_pk_bf16_f32 v165, v128, v129
	s_cmp_lg_u32 0, -1
	s_cselect_b32 s0, 0, 0
	s_add_i32 s0, s0, s90
	s_add_i32 s6, s0, 0xa000
	s_mov_b32 s7, m0
	s_mov_b32 m0, s6
	s_nop 0
	global_load_lds_dwordx4 v[218:219], off
	s_mov_b32 m0, s7
	s_add_i32 s0, s0, 0xc000
	s_mov_b32 s6, m0
	s_mov_b32 m0, s0
	s_nop 0
	global_load_lds_dwordx4 v[220:221], off
	s_mov_b32 m0, s6
	s_waitcnt lgkmcnt(6)
	v_mfma_f32_32x32x16_bf16 v[50:65], v[174:177], v[82:85], v[50:65]
	v_exp_f32_e32 v130, v130
	v_exp_f32_e32 v131, v131
	ds_read_b64_tr_b16 v[66:67], v241 offset:58368
	ds_read_b64_tr_b16 v[68:69], v241 offset:58880
	s_waitcnt lgkmcnt(6)
	v_mfma_f32_32x32x16_bf16 v[34:49], v[174:177], v[70:73], v[34:49]
	v_exp_f32_e32 v132, v132
	v_exp_f32_e32 v133, v133
	ds_read_b64_tr_b16 v[74:75], v241 offset:62464
	ds_read_b64_tr_b16 v[76:77], v241 offset:62976
	s_waitcnt lgkmcnt(6)
	v_mfma_f32_32x32x16_bf16 v[18:33], v[174:177], v[86:89], v[18:33]
	v_exp_f32_e32 v134, v134
	v_exp_f32_e32 v135, v135
	ds_read_b64_tr_b16 v[70:71], v242 offset:41984
	ds_read_b64_tr_b16 v[72:73], v242 offset:42496
	s_waitcnt lgkmcnt(6)
	v_mfma_f32_32x32x16_bf16 v[2:17], v[174:177], v[78:81], v[2:17]
	v_exp_f32_e32 v136, v136
	v_exp_f32_e32 v137, v137
	ds_read_b64_tr_b16 v[82:83], v242 offset:46080
	ds_read_b64_tr_b16 v[84:85], v242 offset:46592
	s_waitcnt lgkmcnt(6)
	v_mfma_f32_32x32x16_bf16 v[50:65], v[170:173], v[66:69], v[50:65]
	v_exp_f32_e32 v138, v138
	v_exp_f32_e32 v139, v139
	ds_read_b64_tr_b16 v[78:79], v241 offset:59392
	ds_read_b64_tr_b16 v[80:81], v241 offset:59904
	s_waitcnt lgkmcnt(6)
	v_mfma_f32_32x32x16_bf16 v[34:49], v[170:173], v[74:77], v[34:49]
	v_exp_f32_e32 v140, v140
	v_exp_f32_e32 v141, v141
	ds_read_b64_tr_b16 v[66:67], v241 offset:63488
	ds_read_b64_tr_b16 v[68:69], v241 offset:64000
	s_waitcnt lgkmcnt(6)
	v_mfma_f32_32x32x16_bf16 v[18:33], v[170:173], v[70:73], v[18:33]
	v_exp_f32_e32 v142, v142
	v_exp_f32_e32 v143, v143
	ds_read_b128 v[74:77], v243 offset:8192
	ds_read_b128 v[86:89], v243 offset:8704
	ds_read_b64_tr_b16 v[90:91], v242 offset:43008
	ds_read_b64_tr_b16 v[92:93], v242 offset:43520
	s_waitcnt lgkmcnt(8)
	v_mfma_f32_32x32x16_bf16 v[2:17], v[170:173], v[82:85], v[2:17]
	v_exp_f32_e32 v144, v144
	v_exp_f32_e32 v145, v145
	ds_read_b64_tr_b16 v[70:71], v242 offset:47104
	ds_read_b64_tr_b16 v[72:73], v242 offset:47616
	s_waitcnt lgkmcnt(8)
	v_mfma_f32_32x32x16_bf16 v[50:65], v[166:169], v[78:81], v[50:65]
	v_exp_f32_e32 v98, v98
	v_exp_f32_e32 v99, v99
	ds_read_b128 v[116:119], v243 offset:10240
	ds_read_b128 v[120:123], v243 offset:10752
	ds_read_b64_tr_b16 v[82:83], v241 offset:60416
	ds_read_b64_tr_b16 v[84:85], v241 offset:60928
	s_waitcnt lgkmcnt(10)
	v_mfma_f32_32x32x16_bf16 v[34:49], v[166:169], v[66:69], v[34:49]
	v_exp_f32_e32 v100, v100
	v_exp_f32_e32 v101, v101
	ds_read_b64_tr_b16 v[78:79], v241 offset:64512
	ds_read_b64_tr_b16 v[80:81], v241 offset:65024
	s_waitcnt lgkmcnt(8)
	v_mfma_f32_32x32x16_bf16 v[18:33], v[166:169], v[90:93], v[18:33]
	v_exp_f32_e32 v102, v102
	v_exp_f32_e32 v103, v103
	ds_read_b128 v[124:127], v243 offset:12288
	ds_read_b128 v[146:149], v243 offset:12800
	ds_read_b64_tr_b16 v[66:67], v242 offset:44032
	ds_read_b64_tr_b16 v[68:69], v242 offset:44544
	s_waitcnt lgkmcnt(10)
	v_mfma_f32_32x32x16_bf16 v[2:17], v[166:169], v[70:73], v[2:17]
	v_exp_f32_e32 v104, v104
	v_exp_f32_e32 v105, v105
	ds_read_b64_tr_b16 v[90:91], v242 offset:48128
	ds_read_b64_tr_b16 v[92:93], v242 offset:48640
	s_waitcnt lgkmcnt(8)
	v_mfma_f32_32x32x16_bf16 v[50:65], v[162:165], v[82:85], v[50:65]
	ds_read_b128 v[150:153], v243 offset:14336
	ds_read_b128 v[154:157], v243 offset:14848
	v_exp_f32_e32 v106, v106
	v_exp_f32_e32 v107, v107
	s_waitcnt lgkmcnt(8)
	v_mfma_f32_32x32x16_bf16 v[34:49], v[162:165], v[78:81], v[34:49]
	v_exp_f32_e32 v108, v108
	v_exp_f32_e32 v109, v109
	s_waitcnt lgkmcnt(4)
	v_mfma_f32_32x32x16_bf16 v[18:33], v[162:165], v[66:69], v[18:33]
	v_exp_f32_e32 v110, v110
	v_exp_f32_e32 v111, v111
	s_waitcnt lgkmcnt(2)
	v_mfma_f32_32x32x16_bf16 v[2:17], v[162:165], v[90:93], v[2:17]
	v_exp_f32_e32 v112, v112
	v_exp_f32_e32 v113, v113
	s_waitcnt vmcnt(0) lgkmcnt(0)
	s_barrier
; #define ATT_WAIT_BAR(N) asm volatile("s_waitcnt vmcnt(" #N ") lgkmcnt(0)\n\ts_barrier" ::: "memory")
; #define ROT() do { sl_prev = sl_cur; sl_cur = sl_next; sl_next = (sl_next == 2) ? 0 : sl_next + 1; } while (0)
; __device__ __forceinline__ void attn_unit(int b, int h, int qb, bool first, bool has_next, int nb, int nh, bf16_t* QO, const bf16_t* __restrict__ K, const bf16_t* __restrict__ V, float lam, char* shm) {
;     ...
;         int t = 1;
; #pragma unroll 1
;         for (; t + 1 <= NT - 4; t += 2) {
;             STEP(pB0, pB1, pA0, pA1, t, true, true, true);     ATT_WAIT_BAR(3); ROT();
;             STEP(pA0, pA1, pB0, pB1, t + 1, true, true, true); ATT_WAIT_BAR(3); ROT();
;         }
;         STEP(pB0, pB1, pA0, pA1, NT - 3, false, true, true);   ATT_WAIT_BAR(2); ROT();
;         STEP(pA0, pA1, pB0, pB1, NT - 2, false, true, true);   ATT_WAIT_BAR(0); ROT();
;         STEP(pB0, pB1, pA0, pA1, NT - 1, false, false, false);
	ds_read_b64_tr_b16 v[158:159], v241 offset:24576
	ds_read_b64_tr_b16 v[160:161], v241 offset:25088
	v_add_f32_e32 v66, v130, v131
	v_add_f32_e32 v66, v132, v66
	v_add_f32_e32 v66, v133, v66
	v_add_f32_e32 v66, v134, v66
	v_add_f32_e32 v82, v135, v66
	v_mfma_f32_32x32x16_bf16 v[66:81], v[74:77], v[190:193], 0
	v_cvt_pk_bf16_f32 v174, v130, v131
	v_cvt_pk_bf16_f32 v175, v132, v133
	ds_read_b64_tr_b16 v[128:129], v241 offset:28672
	ds_read_b64_tr_b16 v[130:131], v241 offset:29184
	v_add_f32_e32 v82, v136, v82
	v_add_f32_e32 v82, v137, v82
	v_add_f32_e32 v82, v138, v82
	v_add_f32_e32 v115, v139, v82
	v_mfma_f32_32x32x16_bf16 v[82:97], v[86:89], v[190:193], 0
	v_cvt_pk_bf16_f32 v176, v134, v135
	v_cvt_pk_bf16_f32 v177, v136, v137
	ds_read_b64_tr_b16 v[132:133], v241 offset:32768
	ds_read_b64_tr_b16 v[134:135], v241 offset:33280
	v_mfma_f32_32x32x16_bf16 v[66:81], v[116:119], v[186:189], v[66:81]
	v_add_f32_e32 v115, v140, v115
	v_add_f32_e32 v115, v141, v115
	v_add_f32_e32 v115, v142, v115
	v_add_f32_e32 v115, v143, v115
	v_cvt_pk_bf16_f32 v170, v138, v139
	v_cvt_pk_bf16_f32 v171, v140, v141
	ds_read_b64_tr_b16 v[116:117], v241 offset:36864
	ds_read_b64_tr_b16 v[118:119], v241 offset:37376
	v_mfma_f32_32x32x16_bf16 v[82:97], v[120:123], v[186:189], v[82:97]
	v_add_f32_e32 v115, v144, v115
	v_add_f32_e32 v115, v145, v115
	v_add_f32_e32 v115, v98, v115
	v_add_f32_e32 v115, v99, v115
	v_cvt_pk_bf16_f32 v172, v142, v143
	v_cvt_pk_bf16_f32 v173, v144, v145
	v_mfma_f32_32x32x16_bf16 v[66:81], v[124:127], v[182:185], v[66:81]
	v_add_f32_e32 v115, v100, v115
	v_add_f32_e32 v115, v101, v115
	v_add_f32_e32 v115, v102, v115
	v_add_f32_e32 v115, v103, v115
	v_cvt_pk_bf16_f32 v166, v98, v99
	v_cvt_pk_bf16_f32 v167, v100, v101
	v_mfma_f32_32x32x16_bf16 v[82:97], v[146:149], v[182:185], v[82:97]
	v_add_f32_e32 v98, v104, v115
	v_add_f32_e32 v98, v105, v98
	v_add_f32_e32 v98, v106, v98
	v_add_f32_e32 v98, v107, v98
	v_cvt_pk_bf16_f32 v168, v102, v103
	v_cvt_pk_bf16_f32 v169, v104, v105
	s_waitcnt lgkmcnt(9)
	v_mfma_f32_32x32x16_bf16 v[66:81], v[150:153], v[178:181], v[66:81]
	v_add_f32_e32 v98, v108, v98
	v_add_f32_e32 v98, v109, v98
	v_add_f32_e32 v98, v110, v98
	v_add_f32_e32 v98, v111, v98
	v_cvt_pk_bf16_f32 v162, v106, v107
	v_cvt_pk_bf16_f32 v163, v108, v109
	s_waitcnt lgkmcnt(8)
	v_mfma_f32_32x32x16_bf16 v[82:97], v[154:157], v[178:181], v[82:97]
	v_add_f32_e32 v98, v112, v98
	v_add_f32_e32 v98, v113, v98
	v_add_f32_e32 v98, 0, v98
	v_cvt_pk_bf16_f32 v164, v110, v111
	v_cvt_pk_bf16_f32 v165, v112, v113
	s_waitcnt lgkmcnt(6)
	v_mfma_f32_32x32x16_bf16 v[50:65], v[174:177], v[158:161], v[50:65]
	v_exp_f32_e32 v66, v66
	v_exp_f32_e32 v67, v67
	ds_read_b64_tr_b16 v[100:101], v241 offset:25600
	ds_read_b64_tr_b16 v[102:103], v241 offset:26112
	s_waitcnt lgkmcnt(6)
	v_mfma_f32_32x32x16_bf16 v[34:49], v[174:177], v[128:131], v[34:49]
	v_exp_f32_e32 v68, v68
	v_exp_f32_e32 v69, v69
	ds_read_b64_tr_b16 v[104:105], v241 offset:29696
	ds_read_b64_tr_b16 v[106:107], v241 offset:30208
	s_waitcnt lgkmcnt(6)
	v_mfma_f32_32x32x16_bf16 v[18:33], v[174:177], v[132:135], v[18:33]
	v_exp_f32_e32 v70, v70
	v_exp_f32_e32 v71, v71
	ds_read_b64_tr_b16 v[108:109], v241 offset:33792
	ds_read_b64_tr_b16 v[110:111], v241 offset:34304
	s_waitcnt lgkmcnt(6)
	v_mfma_f32_32x32x16_bf16 v[2:17], v[174:177], v[116:119], v[2:17]
	v_exp_f32_e32 v72, v72
	v_exp_f32_e32 v73, v73
	ds_read_b64_tr_b16 v[120:121], v241 offset:37888
	ds_read_b64_tr_b16 v[122:123], v241 offset:38400
	s_waitcnt lgkmcnt(6)
	v_mfma_f32_32x32x16_bf16 v[50:65], v[170:173], v[100:103], v[50:65]
	v_exp_f32_e32 v74, v74
	v_exp_f32_e32 v75, v75
	ds_read_b64_tr_b16 v[116:117], v241 offset:26624
	ds_read_b64_tr_b16 v[118:119], v241 offset:27136
	s_waitcnt lgkmcnt(6)
	v_mfma_f32_32x32x16_bf16 v[34:49], v[170:173], v[104:107], v[34:49]
	v_exp_f32_e32 v76, v76
	v_exp_f32_e32 v77, v77
	ds_read_b64_tr_b16 v[100:101], v241 offset:30720
	ds_read_b64_tr_b16 v[102:103], v241 offset:31232
	s_waitcnt lgkmcnt(6)
	v_mfma_f32_32x32x16_bf16 v[18:33], v[170:173], v[108:111], v[18:33]
	v_exp_f32_e32 v78, v78
	v_exp_f32_e32 v79, v79
	ds_read_b64_tr_b16 v[104:105], v241 offset:34816
	ds_read_b64_tr_b16 v[106:107], v241 offset:35328
	s_waitcnt lgkmcnt(6)
	v_mfma_f32_32x32x16_bf16 v[2:17], v[170:173], v[120:123], v[2:17]
	v_exp_f32_e32 v80, v80
	v_exp_f32_e32 v81, v81
	ds_read_b64_tr_b16 v[108:109], v241 offset:38912
	ds_read_b64_tr_b16 v[110:111], v241 offset:39424
	s_waitcnt lgkmcnt(6)
	v_mfma_f32_32x32x16_bf16 v[50:65], v[166:169], v[116:119], v[50:65]
	v_exp_f32_e32 v82, v82
	v_exp_f32_e32 v83, v83
	ds_read_b64_tr_b16 v[120:121], v241 offset:27648
	ds_read_b64_tr_b16 v[122:123], v241 offset:28160
	s_waitcnt lgkmcnt(6)
	v_mfma_f32_32x32x16_bf16 v[34:49], v[166:169], v[100:103], v[34:49]
	v_exp_f32_e32 v84, v84
	v_exp_f32_e32 v85, v85
	ds_read_b64_tr_b16 v[116:117], v241 offset:31744
	ds_read_b64_tr_b16 v[118:119], v241 offset:32256
	s_waitcnt lgkmcnt(6)
	v_mfma_f32_32x32x16_bf16 v[18:33], v[166:169], v[104:107], v[18:33]
	v_exp_f32_e32 v86, v86
	v_exp_f32_e32 v87, v87
	ds_read_b64_tr_b16 v[100:101], v241 offset:35840
	ds_read_b64_tr_b16 v[102:103], v241 offset:36352
	s_waitcnt lgkmcnt(6)
	v_mfma_f32_32x32x16_bf16 v[2:17], v[166:169], v[108:111], v[2:17]
	v_exp_f32_e32 v88, v88
	v_exp_f32_e32 v89, v89
	ds_read_b64_tr_b16 v[104:105], v241 offset:39936
	ds_read_b64_tr_b16 v[106:107], v241 offset:40448
	s_waitcnt lgkmcnt(6)
; __device__ __forceinline__ s16x4 vtr(lds_cptr p) { return __builtin_bit_cast(s16x4, __builtin_amdgcn_ds_read_tr16_b64_v4i16((LAS v4i16_t*)p)); }
; __device__ __forceinline__ void attn_unit(int b, int h, int qb, bool first, bool has_next, int nb, int nh, bf16_t* QO, const bf16_t* __restrict__ K, const bf16_t* __restrict__ V, float lam, char* shm) {
;     ...
;         { float sacc = pB0[0] + pB0[1];
; #pragma unroll
;           for (int r = 2; r < 16; ++r) sacc += pB0[r];
; #pragma unroll
;           for (int r = 0; r < 16; ++r) sacc += pB1[r];
;           l_reg += sacc;
;           pw0 = (u32x4){ATT_PK(pB0[0], pB0[1]), ATT_PK(pB0[2], pB0[3]), ATT_PK(pB0[4], pB0[5]), ATT_PK(pB0[6], pB0[7])};
;           pw1 = (u32x4){ATT_PK(pB0[8], pB0[9]), ATT_PK(pB0[10], pB0[11]), ATT_PK(pB0[12], pB0[13]), ATT_PK(pB0[14], pB0[15])};
;           pw2 = (u32x4){ATT_PK(pB1[0], pB1[1]), ATT_PK(pB1[2], pB1[3]), ATT_PK(pB1[4], pB1[5]), ATT_PK(pB1[6], pB1[7])};
;           pw3 = (u32x4){ATT_PK(pB1[8], pB1[9]), ATT_PK(pB1[10], pB1[11]), ATT_PK(pB1[12], pB1[13]), ATT_PK(pB1[14], pB1[15])};
;           ATT_SB();
;           const lds_cptr vp = vp0 + sl_cur * VSLOT;
; #pragma unroll
;           for (int d0 = 0; d0 < 4; ++d0) {
;               const s16x4 l0 = vtr(vp + d0 * 4096), h0 = vtr(vp + d0 * 4096 + 512), l1 = vtr(vp + d0 * 4096 + 1024), h1 = vtr(vp + d0 * 4096 + 1536);
;               const s16x4 l2 = vtr(vp + d0 * 4096 + 2048), h2 = vtr(vp + d0 * 4096 + 2560), l3 = vtr(vp + d0 * 4096 + 3072), h3 = vtr(vp + d0 * 4096 + 3584);
;               o[d0] = ATT_MFMA(PAF(0), ((bf16x8){l0[0], l0[1], l0[2], l0[3], h0[0], h0[1], h0[2], h0[3]}), o[d0]);
;               o[d0] = ATT_MFMA(PAF(1), ((bf16x8){l1[0], l1[1], l1[2], l1[3], h1[0], h1[1], h1[2], h1[3]}), o[d0]);
;               o[d0] = ATT_MFMA(PAF(2), ((bf16x8){l2[0], l2[1], l2[2], l2[3], h2[0], h2[1], h2[2], h2[3]}), o[d0]);
;               o[d0] = ATT_MFMA(PAF(3), ((bf16x8){l3[0], l3[1], l3[2], l3[3], h3[0], h3[1], h3[2], h3[3]}), o[d0]); } }
;     ...
;         ATT_SB();
;         asm volatile("s_waitcnt lgkmcnt(0)\n\ts_barrier" ::: "memory");
;         ATT_SB();
;         if (map == 0 || has_next) {
;             const bf16_t* nk = (map == 0) ? ksrc + 1024 : K + (long)nb * SEQ * DM + (2 * nh) * 1024 + klane;
;             const bf16_t* nv = (map == 0) ? vsrc0 : V + (long)nb * SEQ * DM + nh * 2048 + vlane;
	v_mfma_f32_32x32x16_bf16 v[50:65], v[162:165], v[120:123], v[50:65]
	v_exp_f32_e32 v90, v90
	v_exp_f32_e32 v91, v91
	s_waitcnt lgkmcnt(4)
	v_mfma_f32_32x32x16_bf16 v[34:49], v[162:165], v[116:119], v[34:49]
	v_exp_f32_e32 v92, v92
	v_exp_f32_e32 v93, v93
	s_waitcnt lgkmcnt(2)
	v_mfma_f32_32x32x16_bf16 v[18:33], v[162:165], v[100:103], v[18:33]
	v_exp_f32_e32 v94, v94
	v_exp_f32_e32 v95, v95
	s_waitcnt lgkmcnt(0)
	v_mfma_f32_32x32x16_bf16 v[2:17], v[162:165], v[104:107], v[2:17]
	v_exp_f32_e32 v96, v96
	v_exp_f32_e32 v97, v97
	v_cvt_pk_bf16_f32 v176, v70, v71
	v_cvt_pk_bf16_f32 v177, v72, v73
	v_cvt_pk_bf16_f32 v172, v78, v79
	v_cvt_pk_bf16_f32 v173, v80, v81
	v_cvt_pk_bf16_f32 v168, v86, v87
	v_cvt_pk_bf16_f32 v169, v88, v89
	v_cvt_pk_bf16_f32 v164, v94, v95
	v_cvt_pk_bf16_f32 v165, v96, v97
	v_cvt_pk_bf16_f32 v174, v66, v67
	v_cvt_pk_bf16_f32 v175, v68, v69
	v_cvt_pk_bf16_f32 v170, v74, v75
	v_cvt_pk_bf16_f32 v171, v76, v77
	v_cvt_pk_bf16_f32 v166, v82, v83
	v_cvt_pk_bf16_f32 v167, v84, v85
	v_cvt_pk_bf16_f32 v162, v90, v91
	v_cvt_pk_bf16_f32 v163, v92, v93
	ds_read_b64_tr_b16 v[100:101], v241 offset:40960
	ds_read_b64_tr_b16 v[102:103], v241 offset:41472
	ds_read_b64_tr_b16 v[104:105], v241 offset:41984
	ds_read_b64_tr_b16 v[106:107], v241 offset:42496
	s_waitcnt lgkmcnt(2)
	v_mfma_f32_32x32x16_bf16 v[50:65], v[174:177], v[100:103], v[50:65]
	s_waitcnt lgkmcnt(0)
	v_mfma_f32_32x32x16_bf16 v[50:65], v[170:173], v[104:107], v[50:65]
	ds_read_b64_tr_b16 v[100:101], v241 offset:43008
	ds_read_b64_tr_b16 v[102:103], v241 offset:43520
	ds_read_b64_tr_b16 v[104:105], v241 offset:44032
	ds_read_b64_tr_b16 v[106:107], v241 offset:44544
	s_waitcnt lgkmcnt(2)
	v_mfma_f32_32x32x16_bf16 v[50:65], v[166:169], v[100:103], v[50:65]
	s_waitcnt lgkmcnt(0)
	v_mfma_f32_32x32x16_bf16 v[50:65], v[162:165], v[104:107], v[50:65]
	ds_read_b64_tr_b16 v[100:101], v241 offset:45056
	ds_read_b64_tr_b16 v[102:103], v241 offset:45568
	ds_read_b64_tr_b16 v[104:105], v241 offset:46080
	ds_read_b64_tr_b16 v[106:107], v241 offset:46592
	s_waitcnt lgkmcnt(2)
	v_mfma_f32_32x32x16_bf16 v[34:49], v[174:177], v[100:103], v[34:49]
	s_waitcnt lgkmcnt(0)
	v_mfma_f32_32x32x16_bf16 v[34:49], v[170:173], v[104:107], v[34:49]
	ds_read_b64_tr_b16 v[100:101], v241 offset:47104
	ds_read_b64_tr_b16 v[102:103], v241 offset:47616
	ds_read_b64_tr_b16 v[104:105], v241 offset:48128
	ds_read_b64_tr_b16 v[106:107], v241 offset:48640
	s_waitcnt lgkmcnt(2)
	v_mfma_f32_32x32x16_bf16 v[34:49], v[166:169], v[100:103], v[34:49]
	s_waitcnt lgkmcnt(0)
	v_mfma_f32_32x32x16_bf16 v[34:49], v[162:165], v[104:107], v[34:49]
	ds_read_b64_tr_b16 v[100:101], v241 offset:49152
	ds_read_b64_tr_b16 v[102:103], v241 offset:49664
	ds_read_b64_tr_b16 v[104:105], v241 offset:50176
	ds_read_b64_tr_b16 v[106:107], v241 offset:50688
	s_waitcnt lgkmcnt(2)
	v_mfma_f32_32x32x16_bf16 v[18:33], v[174:177], v[100:103], v[18:33]
	s_waitcnt lgkmcnt(0)
	v_mfma_f32_32x32x16_bf16 v[18:33], v[170:173], v[104:107], v[18:33]
	ds_read_b64_tr_b16 v[100:101], v241 offset:51200
	ds_read_b64_tr_b16 v[102:103], v241 offset:51712
	ds_read_b64_tr_b16 v[104:105], v241 offset:52224
	ds_read_b64_tr_b16 v[106:107], v241 offset:52736
	s_waitcnt lgkmcnt(2)
	v_mfma_f32_32x32x16_bf16 v[18:33], v[166:169], v[100:103], v[18:33]
	s_waitcnt lgkmcnt(0)
	v_mfma_f32_32x32x16_bf16 v[18:33], v[162:165], v[104:107], v[18:33]
	ds_read_b64_tr_b16 v[100:101], v241 offset:53248
	ds_read_b64_tr_b16 v[102:103], v241 offset:53760
	ds_read_b64_tr_b16 v[104:105], v241 offset:54272
	ds_read_b64_tr_b16 v[106:107], v241 offset:54784
	s_waitcnt lgkmcnt(2)
	v_mfma_f32_32x32x16_bf16 v[2:17], v[174:177], v[100:103], v[2:17]
	s_waitcnt lgkmcnt(0)
	v_mfma_f32_32x32x16_bf16 v[2:17], v[170:173], v[104:107], v[2:17]
	ds_read_b64_tr_b16 v[100:101], v241 offset:55296
	ds_read_b64_tr_b16 v[102:103], v241 offset:55808
	ds_read_b64_tr_b16 v[104:105], v241 offset:56320
	ds_read_b64_tr_b16 v[106:107], v241 offset:56832
	s_waitcnt lgkmcnt(2)
	v_mfma_f32_32x32x16_bf16 v[2:17], v[166:169], v[100:103], v[2:17]
	s_waitcnt lgkmcnt(0)
	v_mfma_f32_32x32x16_bf16 v[2:17], v[162:165], v[104:107], v[2:17]
	s_waitcnt lgkmcnt(0)
	s_barrier
	s_or_b64 s[6:7], s[48:49], s[54:55]
	s_andn2_b64 vcc, exec, s[6:7]
	s_cbranch_vccnz .LBB0_378
	v_lshl_add_u64 v[100:101], v[232:233], 0, s[2:3]
	v_cndmask_b32_e64 v101, v223, v101, s[54:55]
	v_cndmask_b32_e64 v100, v222, v100, s[54:55]
	s_mov_b32 s0, m0
	s_mov_b32 m0, s91
	s_nop 0
	global_load_lds_dwordx4 v[100:101], off
	s_mov_b32 m0, s0
	v_cndmask_b32_e64 v103, v225, v205, s[54:55]
	v_cndmask_b32_e64 v102, v224, v204, s[54:55]
	s_mov_b32 s0, m0
	s_mov_b32 m0, s92
	s_nop 0
	global_load_lds_dwordx4 v[102:103], off
	s_mov_b32 m0, s0
	s_cmp_lg_u32 0, -1
	s_cselect_b32 s0, 0, 0
	s_add_i32 s0, s0, s90
	v_lshl_add_u64 v[102:103], v[102:103], 0, s[2:3]
	s_add_i32 s6, s0, 0x8000
	s_mov_b32 s7, m0
	s_mov_b32 m0, s6
	s_nop 0
	global_load_lds_dwordx4 v[102:103], off
	s_mov_b32 m0, s7
	v_lshl_add_u64 v[102:103], v[100:101], 0, s[4:5]
	s_add_i32 s6, s0, 0x2000
	s_mov_b32 s7, m0
	s_mov_b32 m0, s6
	s_nop 0
	global_load_lds_dwordx4 v[102:103], off
	s_mov_b32 m0, s7
	v_lshl_add_u64 v[100:101], v[100:101], 0, s[22:23]
	s_addk_i32 s0, 0x4000
	s_mov_b32 s6, m0
	s_mov_b32 m0, s0
	s_nop 0
	global_load_lds_dwordx4 v[100:101], off
	s_mov_b32 m0, s6
